# dn_prep: next item's 12 input quads issued right after step 2 into spare registers (in flight across steps 3-4) and copied to their consumer registers at step 5; solve L-row pool shrunk to free them
# baseline (speedup 1.0000x reference)
; DI void dn_prep_fetch(const Params& p, int item, int tid, u32x4 (&pre)[12]) {
;     const int h = item & 7, n = (item >> 3) & 31, b = item >> 8, i = tid >> 3, d0 = (tid & 7) * 8;
;     const bf16_t* DQKV = (const bf16_t*)(p.ws + OFF_DQKV);
; #pragma unroll
;     for (int mat = 0; mat < 3; ++mat)
; #pragma unroll
;         for (int j = 0; j < 4; ++j) { int t = n * 64 + i - 3 + j; t = t < 0 ? 0 : t; pre[mat * 4 + j] = *(const u32x4*)(DQKV + (size_t)(b * SEQL + t) * 1536 + mat * 512 + h * 64 + d0); }
; }
.LBB0_315:
	s_or_b64 exec, exec, s[8:9]
	v_ashrrev_i32_e32 v60, 6, v54
	v_lshlrev_b32_e32 v56, 1, v54
	v_and_b32_e32 v61, 15, v54
	v_lshrrev_b32_e32 v8, 4, v30
	v_cmp_gt_i32_e32 vcc, 20, v60
	s_waitcnt lgkmcnt(0)
	s_barrier
	s_add_i32 s6, s42, s33
	s_cmpk_lt_i32 s6, 0x800
	s_cselect_b32 s5, s6, s42
	s_lshl_b32 s8, s5, 3
	s_lshl_b32 s5, s5, 7
	s_and_b32 s10, s8, 0x7c0
	s_and_b32 s11, s8, 0xfffff800
	s_and_b32 s5, s5, 0x380
	s_add_u32 s8, s29, s5
	s_addc_u32 s9, s40, 0
	v_mov_b32_e32 v35, v165
	s_movk_i32 s5, 0xc00
	v_add_u32_e32 v124, s10, v77
	v_max_i32_e32 v124, 0, v124
	v_add_u32_e32 v124, s11, v124
	v_add3_u32 v122, s10, -3, v77
	v_max_i32_e32 v118, 0, v122
	v_max_i32_e32 v120, -1, v122
	v_max_i32_e32 v122, -2, v122
	v_lshl_add_u64 v[116:117], s[8:9], 0, v[34:35]
	v_add_u32_e32 v118, s11, v118
	v_add3_u32 v120, v120, s11, 1
	v_add3_u32 v122, v122, s11, 2
	v_mad_i64_i32 v[118:119], s[8:9], v118, s5, v[116:117]
	v_mad_i64_i32 v[120:121], s[8:9], v120, s5, v[116:117]
	v_mad_i64_i32 v[122:123], s[8:9], v122, s5, v[116:117]
	v_mad_i64_i32 v[116:117], s[8:9], v124, s5, v[116:117]
	global_load_dwordx4 v[160:163], v[118:119], off
	global_load_dwordx4 v[156:159], v[120:121], off
	global_load_dwordx4 v[152:155], v[122:123], off
	global_load_dwordx4 v[148:151], v[116:117], off
	global_load_dwordx4 v[144:147], v[118:119], off offset:1024
	global_load_dwordx4 v[140:143], v[120:121], off offset:1024
	global_load_dwordx4 v[136:139], v[122:123], off offset:1024
	global_load_dwordx4 v[132:135], v[116:117], off offset:1024
	global_load_dwordx4 v[128:131], v[118:119], off offset:2048
	global_load_dwordx4 v[124:127], v[120:121], off offset:2048
	s_nop 0
	global_load_dwordx4 v[120:123], v[122:123], off offset:2048
	s_nop 0
	global_load_dwordx4 v[116:119], v[116:117], off offset:2048
	s_and_saveexec_b64 s[12:13], vcc
	s_cbranch_execz .LBB0_350
	v_lshlrev_b32_e32 v4, 3, v8
	v_lshlrev_b32_e32 v5, 4, v8
	v_add_u32_e32 v9, v71, v5
	v_add_u32_e32 v10, v72, v5
	v_lshlrev_b32_e32 v11, 2, v8
	s_mov_b64 s[14:15], 0
	v_lshlrev_b32_e32 v12, 1, v4
	v_mov_b32_e32 v13, v60

; DI void dn_prep_item(const Params& p, int l, int item, int next_item, u32x4 (&pre)[12], unsigned char* lds, int tid) {
;     ...
;             f32x4 cur[8], nxt[8];
;             cur[0] = *(const f32x4*)(Lb + 64);
; #pragma unroll
;             for (int i = 1; i < 32; ++i) {
;                 if (i < 31) {
; #pragma unroll
;                     for (int q = 0; q < 8; ++q) if (4 * q < i + 1) nxt[q] = *(const f32x4*)(Lb + (i + 1) * 64 + 4 * q);
;                 }
;                 float a0 = x[i], a1 = 0.f, a2 = 0.f, a3 = 0.f;
; #pragma unroll
;                 for (int j = 0; j < i; ++j) { const float lv = cur[j >> 2][j & 3];
;                     if ((j & 3) == 0) a0 -= lv * x[j]; else if ((j & 3) == 1) a1 -= lv * x[j]; else if ((j & 3) == 2) a2 -= lv * x[j]; else a3 -= lv * x[j]; }
;                 x[i] = (a0 + a1) + (a2 + a3);
; #pragma unroll
;                 for (int q = 0; q < 8; ++q) cur[q] = nxt[q];
;             }
.LBB0_496:
	s_or_b64 exec, exec, s[6:7]
	s_waitcnt lgkmcnt(0)
	v_mov_b32_e32 v46, 0
	v_mov_b32_e32 v47, 0
	ds_read_b128 v[78:81], v35 offset:50176
	ds_read_b128 v[82:85], v35 offset:50432
	ds_read_b128 v[86:89], v35 offset:50688
	ds_read_b128 v[90:93], v35 offset:50944
	s_waitcnt lgkmcnt(3)
	v_fma_f32 v1, -v78, v0, v1
	v_add_f32_e32 v1, 0, v1
	s_waitcnt lgkmcnt(2)
	v_fma_f32 v38, -v82, v0, v2
	v_fma_f32 v39, -v83, v1, 0
	ds_read_b128 v[94:97], v35 offset:51200
	ds_read_b128 v[98:101], v35 offset:51216
	v_add_f32_e32 v2, v38, v39
	s_waitcnt lgkmcnt(3)
	v_fma_f32 v42, -v86, v0, v3
	v_fma_f32 v43, -v87, v1, 0
	v_fma_f32 v44, -v88, v2, 0
	ds_read_b128 v[102:105], v35 offset:51456
	ds_read_b128 v[106:109], v35 offset:51472
	v_add_f32_e32 v42, v42, v43
	v_add_f32_e32 v3, v42, v44
	s_waitcnt lgkmcnt(4)
	v_fma_f32 v38, -v90, v0, v4
	v_fma_f32 v39, -v91, v1, 0
	v_pk_fma_f32 v[40:41], v[92:93], v[2:3], v[46:47] neg_lo:[1,0,0] neg_hi:[1,0,0]
	ds_read_b128 v[110:113], v35 offset:51712
	ds_read_b128 v[212:215], v35 offset:51728
	v_add_f32_e32 v38, v39, v38
	v_add_f32_e32 v40, v40, v41
	v_add_f32_e32 v4, v38, v40
	s_waitcnt lgkmcnt(4)
	v_fma_f32 v42, -v94, v0, v5
	v_fma_f32 v43, -v95, v1, 0
	v_pk_fma_f32 v[44:45], v[96:97], v[2:3], v[46:47] neg_lo:[1,0,0] neg_hi:[1,0,0]
	ds_read_b128 v[216:219], v35 offset:51968
	ds_read_b128 v[220:223], v35 offset:51984
	v_pk_fma_f32 v[42:43], v[98:99], v[4:5], v[42:43] neg_lo:[1,0,0] neg_hi:[1,0,0]
	s_waitcnt lgkmcnt(4)
	v_fma_f32 v38, -v102, v0, v6
	v_add_f32_e32 v42, v43, v42
	v_fma_f32 v39, -v103, v1, 0
	v_add_f32_e32 v44, v44, v45
	v_pk_fma_f32 v[40:41], v[104:105], v[2:3], v[46:47] neg_lo:[1,0,0] neg_hi:[1,0,0]
	v_add_f32_e32 v5, v42, v44
	ds_read_b128 v[224:227], v35 offset:52224
	ds_read_b128 v[228:231], v35 offset:52240
	ds_read_b128 v[232:235], v35 offset:52256
	v_pk_fma_f32 v[38:39], v[106:107], v[4:5], v[38:39] neg_lo:[1,0,0] neg_hi:[1,0,0]
	s_waitcnt lgkmcnt(5)
	v_fma_f32 v42, -v110, v0, v7
	v_add_f32_e32 v38, v39, v38
	v_fma_f32 v43, -v111, v1, 0
	v_add_f32_e32 v40, v40, v41
	v_pk_fma_f32 v[44:45], v[112:113], v[2:3], v[46:47] neg_lo:[1,0,0] neg_hi:[1,0,0]
	v_add_f32_e32 v6, v38, v40
	ds_read_b128 v[236:239], v35 offset:52480
	ds_read_b128 v[240:243], v35 offset:52496
	ds_read_b128 v[62:65], v35 offset:52512
	v_pk_fma_f32 v[42:43], v[212:213], v[4:5], v[42:43] neg_lo:[1,0,0] neg_hi:[1,0,0]
	v_pk_fma_f32 v[44:45], v[214:215], v[6:7], v[44:45] neg_lo:[1,0,0] neg_hi:[1,0,0]
	s_waitcnt lgkmcnt(6)
	v_fma_f32 v38, -v216, v0, v8
	v_add_f32_e32 v42, v43, v42
	v_fma_f32 v39, -v217, v1, 0
	v_add_f32_e32 v44, v44, v45
	v_pk_fma_f32 v[40:41], v[218:219], v[2:3], v[46:47] neg_lo:[1,0,0] neg_hi:[1,0,0]
	v_add_f32_e32 v7, v42, v44
	ds_read_b128 v[78:81], v35 offset:52736
	ds_read_b128 v[82:85], v35 offset:52752
	ds_read_b128 v[86:89], v35 offset:52768
	v_pk_fma_f32 v[38:39], v[220:221], v[4:5], v[38:39] neg_lo:[1,0,0] neg_hi:[1,0,0]
	v_pk_fma_f32 v[40:41], v[222:223], v[6:7], v[40:41] neg_lo:[1,0,0] neg_hi:[1,0,0]
	s_waitcnt lgkmcnt(6)
	v_fma_f32 v42, -v224, v0, v9
	v_add_f32_e32 v38, v39, v38
	v_fma_f32 v43, -v225, v1, 0
	v_add_f32_e32 v40, v40, v41
	v_pk_fma_f32 v[44:45], v[226:227], v[2:3], v[46:47] neg_lo:[1,0,0] neg_hi:[1,0,0]
	v_add_f32_e32 v8, v38, v40
	ds_read_b128 v[90:93], v35 offset:52992
	ds_read_b128 v[94:97], v35 offset:53008
	ds_read_b128 v[98:101], v35 offset:53024
	v_pk_fma_f32 v[42:43], v[228:229], v[4:5], v[42:43] neg_lo:[1,0,0] neg_hi:[1,0,0]
	v_pk_fma_f32 v[44:45], v[230:231], v[6:7], v[44:45] neg_lo:[1,0,0] neg_hi:[1,0,0]
	v_pk_fma_f32 v[42:43], v[232:233], v[8:9], v[42:43] neg_lo:[1,0,0] neg_hi:[1,0,0]
	s_waitcnt lgkmcnt(6)
	v_fma_f32 v38, -v236, v0, v10
	v_add_f32_e32 v42, v43, v42
	v_fma_f32 v39, -v237, v1, 0
	v_add_f32_e32 v44, v44, v45
	v_pk_fma_f32 v[40:41], v[238:239], v[2:3], v[46:47] neg_lo:[1,0,0] neg_hi:[1,0,0]
	v_add_f32_e32 v9, v42, v44
	ds_read_b128 v[102:105], v35 offset:53248
	ds_read_b128 v[106:109], v35 offset:53264
	ds_read_b128 v[110:113], v35 offset:53280
	ds_read_b128 v[212:215], v35 offset:53296
	v_pk_fma_f32 v[38:39], v[240:241], v[4:5], v[38:39] neg_lo:[1,0,0] neg_hi:[1,0,0]
	v_pk_fma_f32 v[40:41], v[242:243], v[6:7], v[40:41] neg_lo:[1,0,0] neg_hi:[1,0,0]
	v_pk_fma_f32 v[38:39], v[62:63], v[8:9], v[38:39] neg_lo:[1,0,0] neg_hi:[1,0,0]
	s_waitcnt lgkmcnt(7)
	v_fma_f32 v42, -v78, v0, v11
	v_add_f32_e32 v38, v39, v38
	v_fma_f32 v43, -v79, v1, 0
	v_add_f32_e32 v40, v40, v41
	v_pk_fma_f32 v[44:45], v[80:81], v[2:3], v[46:47] neg_lo:[1,0,0] neg_hi:[1,0,0]
	v_add_f32_e32 v10, v38, v40
	ds_read_b128 v[216:219], v35 offset:53504
	ds_read_b128 v[220:223], v35 offset:53520
	ds_read_b128 v[224:227], v35 offset:53536
	ds_read_b128 v[228:231], v35 offset:53552
	v_pk_fma_f32 v[42:43], v[82:83], v[4:5], v[42:43] neg_lo:[1,0,0] neg_hi:[1,0,0]
	v_pk_fma_f32 v[44:45], v[84:85], v[6:7], v[44:45] neg_lo:[1,0,0] neg_hi:[1,0,0]
	v_pk_fma_f32 v[42:43], v[86:87], v[8:9], v[42:43] neg_lo:[1,0,0] neg_hi:[1,0,0]
	v_pk_fma_f32 v[44:45], v[88:89], v[10:11], v[44:45] neg_lo:[1,0,0] neg_hi:[1,0,0]
	s_waitcnt lgkmcnt(8)
	v_fma_f32 v38, -v90, v0, v12
	v_add_f32_e32 v42, v43, v42
	v_fma_f32 v39, -v91, v1, 0
	v_add_f32_e32 v44, v44, v45
	v_pk_fma_f32 v[40:41], v[92:93], v[2:3], v[46:47] neg_lo:[1,0,0] neg_hi:[1,0,0]
	v_add_f32_e32 v11, v42, v44
	ds_read_b128 v[232:235], v35 offset:53760
	ds_read_b128 v[236:239], v35 offset:53776
	ds_read_b128 v[240:243], v35 offset:53792
	ds_read_b128 v[62:65], v35 offset:53808
	v_pk_fma_f32 v[38:39], v[94:95], v[4:5], v[38:39] neg_lo:[1,0,0] neg_hi:[1,0,0]
	v_pk_fma_f32 v[40:41], v[96:97], v[6:7], v[40:41] neg_lo:[1,0,0] neg_hi:[1,0,0]
	v_pk_fma_f32 v[38:39], v[98:99], v[8:9], v[38:39] neg_lo:[1,0,0] neg_hi:[1,0,0]
	v_pk_fma_f32 v[40:41], v[100:101], v[10:11], v[40:41] neg_lo:[1,0,0] neg_hi:[1,0,0]
	s_waitcnt lgkmcnt(8)
; DI void dn_prep_item(const Params& p, int l, int item, int next_item, u32x4 (&pre)[12], unsigned char* lds, int tid) {
;     ...
;             f32x4 cur[8], nxt[8];
;             cur[0] = *(const f32x4*)(Lb + 64);
; #pragma unroll
;             for (int i = 1; i < 32; ++i) {
;                 if (i < 31) {
; #pragma unroll
;                     for (int q = 0; q < 8; ++q) if (4 * q < i + 1) nxt[q] = *(const f32x4*)(Lb + (i + 1) * 64 + 4 * q);
;                 }
;                 float a0 = x[i], a1 = 0.f, a2 = 0.f, a3 = 0.f;
; #pragma unroll
;                 for (int j = 0; j < i; ++j) { const float lv = cur[j >> 2][j & 3];
;                     if ((j & 3) == 0) a0 -= lv * x[j]; else if ((j & 3) == 1) a1 -= lv * x[j]; else if ((j & 3) == 2) a2 -= lv * x[j]; else a3 -= lv * x[j]; }
;                 x[i] = (a0 + a1) + (a2 + a3);
; #pragma unroll
;                 for (int q = 0; q < 8; ++q) cur[q] = nxt[q];
;             }
	v_fma_f32 v42, -v102, v0, v13
	v_add_f32_e32 v38, v39, v38
	v_fma_f32 v43, -v103, v1, 0
	v_add_f32_e32 v40, v40, v41
	v_pk_fma_f32 v[44:45], v[104:105], v[2:3], v[46:47] neg_lo:[1,0,0] neg_hi:[1,0,0]
	v_add_f32_e32 v12, v38, v40
	ds_read_b128 v[78:81], v35 offset:54016
	ds_read_b128 v[82:85], v35 offset:54032
	ds_read_b128 v[86:89], v35 offset:54048
	ds_read_b128 v[90:93], v35 offset:54064
	v_pk_fma_f32 v[42:43], v[106:107], v[4:5], v[42:43] neg_lo:[1,0,0] neg_hi:[1,0,0]
	v_pk_fma_f32 v[44:45], v[108:109], v[6:7], v[44:45] neg_lo:[1,0,0] neg_hi:[1,0,0]
	v_pk_fma_f32 v[42:43], v[110:111], v[8:9], v[42:43] neg_lo:[1,0,0] neg_hi:[1,0,0]
	v_pk_fma_f32 v[44:45], v[112:113], v[10:11], v[44:45] neg_lo:[1,0,0] neg_hi:[1,0,0]
	v_pk_fma_f32 v[42:43], v[212:213], v[12:13], v[42:43] neg_lo:[1,0,0] neg_hi:[1,0,0]
	s_waitcnt lgkmcnt(8)
	v_fma_f32 v38, -v216, v0, v14
	v_add_f32_e32 v42, v43, v42
	v_fma_f32 v39, -v217, v1, 0
	v_add_f32_e32 v44, v44, v45
	v_pk_fma_f32 v[40:41], v[218:219], v[2:3], v[46:47] neg_lo:[1,0,0] neg_hi:[1,0,0]
	v_add_f32_e32 v13, v42, v44
	v_pk_fma_f32 v[38:39], v[220:221], v[4:5], v[38:39] neg_lo:[1,0,0] neg_hi:[1,0,0]
	v_pk_fma_f32 v[40:41], v[222:223], v[6:7], v[40:41] neg_lo:[1,0,0] neg_hi:[1,0,0]
	v_pk_fma_f32 v[38:39], v[224:225], v[8:9], v[38:39] neg_lo:[1,0,0] neg_hi:[1,0,0]
	v_pk_fma_f32 v[40:41], v[226:227], v[10:11], v[40:41] neg_lo:[1,0,0] neg_hi:[1,0,0]
	v_pk_fma_f32 v[38:39], v[228:229], v[12:13], v[38:39] neg_lo:[1,0,0] neg_hi:[1,0,0]
	s_waitcnt lgkmcnt(4)
	v_fma_f32 v42, -v232, v0, v15
	v_add_f32_e32 v38, v39, v38
	v_fma_f32 v43, -v233, v1, 0
	v_add_f32_e32 v40, v40, v41
	v_pk_fma_f32 v[44:45], v[234:235], v[2:3], v[46:47] neg_lo:[1,0,0] neg_hi:[1,0,0]
	v_add_f32_e32 v14, v38, v40
	ds_read_b128 v[94:97], v35 offset:54272
	ds_read_b128 v[98:101], v35 offset:54288
	ds_read_b128 v[102:105], v35 offset:54304
	ds_read_b128 v[106:109], v35 offset:54320
	ds_read_b128 v[110:113], v35 offset:54336
	v_pk_fma_f32 v[42:43], v[236:237], v[4:5], v[42:43] neg_lo:[1,0,0] neg_hi:[1,0,0]
	v_pk_fma_f32 v[44:45], v[238:239], v[6:7], v[44:45] neg_lo:[1,0,0] neg_hi:[1,0,0]
	v_pk_fma_f32 v[42:43], v[240:241], v[8:9], v[42:43] neg_lo:[1,0,0] neg_hi:[1,0,0]
	v_pk_fma_f32 v[44:45], v[242:243], v[10:11], v[44:45] neg_lo:[1,0,0] neg_hi:[1,0,0]
	v_pk_fma_f32 v[42:43], v[62:63], v[12:13], v[42:43] neg_lo:[1,0,0] neg_hi:[1,0,0]
	v_pk_fma_f32 v[44:45], v[64:65], v[14:15], v[44:45] neg_lo:[1,0,0] neg_hi:[1,0,0]
	s_waitcnt lgkmcnt(5)
	v_fma_f32 v38, -v78, v0, v16
	v_add_f32_e32 v42, v43, v42
	v_fma_f32 v39, -v79, v1, 0
	v_add_f32_e32 v44, v44, v45
	v_pk_fma_f32 v[40:41], v[80:81], v[2:3], v[46:47] neg_lo:[1,0,0] neg_hi:[1,0,0]
	v_add_f32_e32 v15, v42, v44
	ds_read_b128 v[212:215], v35 offset:54528
	ds_read_b128 v[216:219], v35 offset:54544
	ds_read_b128 v[220:223], v35 offset:54560
	ds_read_b128 v[224:227], v35 offset:54576
	ds_read_b128 v[228:231], v35 offset:54592
	v_pk_fma_f32 v[38:39], v[82:83], v[4:5], v[38:39] neg_lo:[1,0,0] neg_hi:[1,0,0]
	v_pk_fma_f32 v[40:41], v[84:85], v[6:7], v[40:41] neg_lo:[1,0,0] neg_hi:[1,0,0]
	v_pk_fma_f32 v[38:39], v[86:87], v[8:9], v[38:39] neg_lo:[1,0,0] neg_hi:[1,0,0]
	v_pk_fma_f32 v[40:41], v[88:89], v[10:11], v[40:41] neg_lo:[1,0,0] neg_hi:[1,0,0]
	v_pk_fma_f32 v[38:39], v[90:91], v[12:13], v[38:39] neg_lo:[1,0,0] neg_hi:[1,0,0]
	v_pk_fma_f32 v[40:41], v[92:93], v[14:15], v[40:41] neg_lo:[1,0,0] neg_hi:[1,0,0]
	s_waitcnt lgkmcnt(5)
	v_fma_f32 v42, -v94, v0, v17
	v_add_f32_e32 v38, v39, v38
	v_fma_f32 v43, -v95, v1, 0
	v_add_f32_e32 v40, v40, v41
	v_pk_fma_f32 v[44:45], v[96:97], v[2:3], v[46:47] neg_lo:[1,0,0] neg_hi:[1,0,0]
	v_add_f32_e32 v16, v38, v40
	ds_read_b128 v[232:235], v35 offset:54784
	ds_read_b128 v[236:239], v35 offset:54800
	ds_read_b128 v[240:243], v35 offset:54816
	ds_read_b128 v[62:65], v35 offset:54832
	ds_read_b128 v[78:81], v35 offset:54848
	v_pk_fma_f32 v[42:43], v[98:99], v[4:5], v[42:43] neg_lo:[1,0,0] neg_hi:[1,0,0]
	v_pk_fma_f32 v[44:45], v[100:101], v[6:7], v[44:45] neg_lo:[1,0,0] neg_hi:[1,0,0]
	v_pk_fma_f32 v[42:43], v[102:103], v[8:9], v[42:43] neg_lo:[1,0,0] neg_hi:[1,0,0]
	v_pk_fma_f32 v[44:45], v[104:105], v[10:11], v[44:45] neg_lo:[1,0,0] neg_hi:[1,0,0]
	v_pk_fma_f32 v[42:43], v[106:107], v[12:13], v[42:43] neg_lo:[1,0,0] neg_hi:[1,0,0]
	v_pk_fma_f32 v[44:45], v[108:109], v[14:15], v[44:45] neg_lo:[1,0,0] neg_hi:[1,0,0]
	v_pk_fma_f32 v[42:43], v[110:111], v[16:17], v[42:43] neg_lo:[1,0,0] neg_hi:[1,0,0]
	s_waitcnt lgkmcnt(5)
	v_fma_f32 v38, -v212, v0, v18
	v_add_f32_e32 v42, v43, v42
	v_fma_f32 v39, -v213, v1, 0
	v_add_f32_e32 v44, v44, v45
	v_pk_fma_f32 v[40:41], v[214:215], v[2:3], v[46:47] neg_lo:[1,0,0] neg_hi:[1,0,0]
	v_add_f32_e32 v17, v42, v44
	ds_read_b128 v[82:85], v35 offset:55040
	ds_read_b128 v[86:89], v35 offset:55056
	ds_read_b128 v[90:93], v35 offset:55072
	ds_read_b128 v[94:97], v35 offset:55088
	ds_read_b128 v[98:101], v35 offset:55104
	v_pk_fma_f32 v[38:39], v[216:217], v[4:5], v[38:39] neg_lo:[1,0,0] neg_hi:[1,0,0]
	v_pk_fma_f32 v[40:41], v[218:219], v[6:7], v[40:41] neg_lo:[1,0,0] neg_hi:[1,0,0]
	v_pk_fma_f32 v[38:39], v[220:221], v[8:9], v[38:39] neg_lo:[1,0,0] neg_hi:[1,0,0]
	v_pk_fma_f32 v[40:41], v[222:223], v[10:11], v[40:41] neg_lo:[1,0,0] neg_hi:[1,0,0]
	v_pk_fma_f32 v[38:39], v[224:225], v[12:13], v[38:39] neg_lo:[1,0,0] neg_hi:[1,0,0]
	v_pk_fma_f32 v[40:41], v[226:227], v[14:15], v[40:41] neg_lo:[1,0,0] neg_hi:[1,0,0]
	v_pk_fma_f32 v[38:39], v[228:229], v[16:17], v[38:39] neg_lo:[1,0,0] neg_hi:[1,0,0]
	s_waitcnt lgkmcnt(5)
; DI void dn_prep_item(const Params& p, int l, int item, int next_item, u32x4 (&pre)[12], unsigned char* lds, int tid) {
;     ...
;             f32x4 cur[8], nxt[8];
;             cur[0] = *(const f32x4*)(Lb + 64);
; #pragma unroll
;             for (int i = 1; i < 32; ++i) {
;                 if (i < 31) {
; #pragma unroll
;                     for (int q = 0; q < 8; ++q) if (4 * q < i + 1) nxt[q] = *(const f32x4*)(Lb + (i + 1) * 64 + 4 * q);
;                 }
;                 float a0 = x[i], a1 = 0.f, a2 = 0.f, a3 = 0.f;
; #pragma unroll
;                 for (int j = 0; j < i; ++j) { const float lv = cur[j >> 2][j & 3];
;                     if ((j & 3) == 0) a0 -= lv * x[j]; else if ((j & 3) == 1) a1 -= lv * x[j]; else if ((j & 3) == 2) a2 -= lv * x[j]; else a3 -= lv * x[j]; }
;                 x[i] = (a0 + a1) + (a2 + a3);
; #pragma unroll
;                 for (int q = 0; q < 8; ++q) cur[q] = nxt[q];
;             }
	v_fma_f32 v42, -v232, v0, v19
	v_add_f32_e32 v38, v39, v38
	v_fma_f32 v43, -v233, v1, 0
	v_add_f32_e32 v40, v40, v41
	v_pk_fma_f32 v[44:45], v[234:235], v[2:3], v[46:47] neg_lo:[1,0,0] neg_hi:[1,0,0]
	v_add_f32_e32 v18, v38, v40
	ds_read_b128 v[102:105], v35 offset:55296
	ds_read_b128 v[106:109], v35 offset:55312
	ds_read_b128 v[110:113], v35 offset:55328
	ds_read_b128 v[212:215], v35 offset:55344
	ds_read_b128 v[216:219], v35 offset:55360
	ds_read_b128 v[220:223], v35 offset:55376
	v_pk_fma_f32 v[42:43], v[236:237], v[4:5], v[42:43] neg_lo:[1,0,0] neg_hi:[1,0,0]
	v_pk_fma_f32 v[44:45], v[238:239], v[6:7], v[44:45] neg_lo:[1,0,0] neg_hi:[1,0,0]
	v_pk_fma_f32 v[42:43], v[240:241], v[8:9], v[42:43] neg_lo:[1,0,0] neg_hi:[1,0,0]
	v_pk_fma_f32 v[44:45], v[242:243], v[10:11], v[44:45] neg_lo:[1,0,0] neg_hi:[1,0,0]
	v_pk_fma_f32 v[42:43], v[62:63], v[12:13], v[42:43] neg_lo:[1,0,0] neg_hi:[1,0,0]
	v_pk_fma_f32 v[44:45], v[64:65], v[14:15], v[44:45] neg_lo:[1,0,0] neg_hi:[1,0,0]
	v_pk_fma_f32 v[42:43], v[78:79], v[16:17], v[42:43] neg_lo:[1,0,0] neg_hi:[1,0,0]
	v_pk_fma_f32 v[44:45], v[80:81], v[18:19], v[44:45] neg_lo:[1,0,0] neg_hi:[1,0,0]
	s_waitcnt lgkmcnt(6)
	v_fma_f32 v38, -v82, v0, v20
	v_add_f32_e32 v42, v43, v42
	v_fma_f32 v39, -v83, v1, 0
	v_add_f32_e32 v44, v44, v45
	v_pk_fma_f32 v[40:41], v[84:85], v[2:3], v[46:47] neg_lo:[1,0,0] neg_hi:[1,0,0]
	v_add_f32_e32 v19, v42, v44
	ds_read_b128 v[224:227], v35 offset:55552
	ds_read_b128 v[228:231], v35 offset:55568
	ds_read_b128 v[232:235], v35 offset:55584
	ds_read_b128 v[236:239], v35 offset:55600
	ds_read_b128 v[240:243], v35 offset:55616
	ds_read_b128 v[62:65], v35 offset:55632
	v_pk_fma_f32 v[38:39], v[86:87], v[4:5], v[38:39] neg_lo:[1,0,0] neg_hi:[1,0,0]
	v_pk_fma_f32 v[40:41], v[88:89], v[6:7], v[40:41] neg_lo:[1,0,0] neg_hi:[1,0,0]
	v_pk_fma_f32 v[38:39], v[90:91], v[8:9], v[38:39] neg_lo:[1,0,0] neg_hi:[1,0,0]
	v_pk_fma_f32 v[40:41], v[92:93], v[10:11], v[40:41] neg_lo:[1,0,0] neg_hi:[1,0,0]
	v_pk_fma_f32 v[38:39], v[94:95], v[12:13], v[38:39] neg_lo:[1,0,0] neg_hi:[1,0,0]
	v_pk_fma_f32 v[40:41], v[96:97], v[14:15], v[40:41] neg_lo:[1,0,0] neg_hi:[1,0,0]
	v_pk_fma_f32 v[38:39], v[98:99], v[16:17], v[38:39] neg_lo:[1,0,0] neg_hi:[1,0,0]
	v_pk_fma_f32 v[40:41], v[100:101], v[18:19], v[40:41] neg_lo:[1,0,0] neg_hi:[1,0,0]
	s_waitcnt lgkmcnt(6)
	v_fma_f32 v42, -v102, v0, v21
	v_add_f32_e32 v38, v39, v38
	v_fma_f32 v43, -v103, v1, 0
	v_add_f32_e32 v40, v40, v41
	v_pk_fma_f32 v[44:45], v[104:105], v[2:3], v[46:47] neg_lo:[1,0,0] neg_hi:[1,0,0]
	v_add_f32_e32 v20, v38, v40
	ds_read_b128 v[78:81], v35 offset:55808
	ds_read_b128 v[82:85], v35 offset:55824
	ds_read_b128 v[86:89], v35 offset:55840
	ds_read_b128 v[90:93], v35 offset:55856
	ds_read_b128 v[94:97], v35 offset:55872
	ds_read_b128 v[98:101], v35 offset:55888
	v_pk_fma_f32 v[42:43], v[106:107], v[4:5], v[42:43] neg_lo:[1,0,0] neg_hi:[1,0,0]
	v_pk_fma_f32 v[44:45], v[108:109], v[6:7], v[44:45] neg_lo:[1,0,0] neg_hi:[1,0,0]
	v_pk_fma_f32 v[42:43], v[110:111], v[8:9], v[42:43] neg_lo:[1,0,0] neg_hi:[1,0,0]
	v_pk_fma_f32 v[44:45], v[112:113], v[10:11], v[44:45] neg_lo:[1,0,0] neg_hi:[1,0,0]
	v_pk_fma_f32 v[42:43], v[212:213], v[12:13], v[42:43] neg_lo:[1,0,0] neg_hi:[1,0,0]
	v_pk_fma_f32 v[44:45], v[214:215], v[14:15], v[44:45] neg_lo:[1,0,0] neg_hi:[1,0,0]
	v_pk_fma_f32 v[42:43], v[216:217], v[16:17], v[42:43] neg_lo:[1,0,0] neg_hi:[1,0,0]
	v_pk_fma_f32 v[44:45], v[218:219], v[18:19], v[44:45] neg_lo:[1,0,0] neg_hi:[1,0,0]
	v_pk_fma_f32 v[42:43], v[220:221], v[20:21], v[42:43] neg_lo:[1,0,0] neg_hi:[1,0,0]
	s_waitcnt lgkmcnt(6)
	v_fma_f32 v38, -v224, v0, v22
	v_add_f32_e32 v42, v43, v42
	v_fma_f32 v39, -v225, v1, 0
	v_add_f32_e32 v44, v44, v45
	v_pk_fma_f32 v[40:41], v[226:227], v[2:3], v[46:47] neg_lo:[1,0,0] neg_hi:[1,0,0]
	v_add_f32_e32 v21, v42, v44
	ds_read_b128 v[102:105], v35 offset:56064
	ds_read_b128 v[106:109], v35 offset:56080
	ds_read_b128 v[110:113], v35 offset:56096
	ds_read_b128 v[212:215], v35 offset:56112
	ds_read_b128 v[216:219], v35 offset:56128
	ds_read_b128 v[220:223], v35 offset:56144
	v_pk_fma_f32 v[38:39], v[228:229], v[4:5], v[38:39] neg_lo:[1,0,0] neg_hi:[1,0,0]
	v_pk_fma_f32 v[40:41], v[230:231], v[6:7], v[40:41] neg_lo:[1,0,0] neg_hi:[1,0,0]
	v_pk_fma_f32 v[38:39], v[232:233], v[8:9], v[38:39] neg_lo:[1,0,0] neg_hi:[1,0,0]
	v_pk_fma_f32 v[40:41], v[234:235], v[10:11], v[40:41] neg_lo:[1,0,0] neg_hi:[1,0,0]
	v_pk_fma_f32 v[38:39], v[236:237], v[12:13], v[38:39] neg_lo:[1,0,0] neg_hi:[1,0,0]
	v_pk_fma_f32 v[40:41], v[238:239], v[14:15], v[40:41] neg_lo:[1,0,0] neg_hi:[1,0,0]
	v_pk_fma_f32 v[38:39], v[240:241], v[16:17], v[38:39] neg_lo:[1,0,0] neg_hi:[1,0,0]
	v_pk_fma_f32 v[40:41], v[242:243], v[18:19], v[40:41] neg_lo:[1,0,0] neg_hi:[1,0,0]
	v_pk_fma_f32 v[38:39], v[62:63], v[20:21], v[38:39] neg_lo:[1,0,0] neg_hi:[1,0,0]
	s_waitcnt lgkmcnt(6)
	v_fma_f32 v42, -v78, v0, v23
	v_add_f32_e32 v38, v39, v38
	v_fma_f32 v43, -v79, v1, 0
	v_add_f32_e32 v40, v40, v41
	v_pk_fma_f32 v[44:45], v[80:81], v[2:3], v[46:47] neg_lo:[1,0,0] neg_hi:[1,0,0]
	v_add_f32_e32 v22, v38, v40
	v_pk_fma_f32 v[42:43], v[82:83], v[4:5], v[42:43] neg_lo:[1,0,0] neg_hi:[1,0,0]
	v_pk_fma_f32 v[44:45], v[84:85], v[6:7], v[44:45] neg_lo:[1,0,0] neg_hi:[1,0,0]
	v_pk_fma_f32 v[42:43], v[86:87], v[8:9], v[42:43] neg_lo:[1,0,0] neg_hi:[1,0,0]
	v_pk_fma_f32 v[44:45], v[88:89], v[10:11], v[44:45] neg_lo:[1,0,0] neg_hi:[1,0,0]
	v_pk_fma_f32 v[42:43], v[90:91], v[12:13], v[42:43] neg_lo:[1,0,0] neg_hi:[1,0,0]
	v_pk_fma_f32 v[44:45], v[92:93], v[14:15], v[44:45] neg_lo:[1,0,0] neg_hi:[1,0,0]
	v_pk_fma_f32 v[42:43], v[94:95], v[16:17], v[42:43] neg_lo:[1,0,0] neg_hi:[1,0,0]
	v_pk_fma_f32 v[44:45], v[96:97], v[18:19], v[44:45] neg_lo:[1,0,0] neg_hi:[1,0,0]
	v_pk_fma_f32 v[42:43], v[98:99], v[20:21], v[42:43] neg_lo:[1,0,0] neg_hi:[1,0,0]
	v_pk_fma_f32 v[44:45], v[100:101], v[22:23], v[44:45] neg_lo:[1,0,0] neg_hi:[1,0,0]
	s_waitcnt lgkmcnt(0)
; DI void dn_prep_item(const Params& p, int l, int item, int next_item, u32x4 (&pre)[12], unsigned char* lds, int tid) {
;     ...
;             for (int i = 1; i < 32; ++i) {
;                 if (i < 31) {
; #pragma unroll
;                     for (int q = 0; q < 8; ++q) if (4 * q < i + 1) nxt[q] = *(const f32x4*)(Lb + (i + 1) * 64 + 4 * q);
;                 }
;                 float a0 = x[i], a1 = 0.f, a2 = 0.f, a3 = 0.f;
; #pragma unroll
;                 for (int j = 0; j < i; ++j) { const float lv = cur[j >> 2][j & 3];
;                     if ((j & 3) == 0) a0 -= lv * x[j]; else if ((j & 3) == 1) a1 -= lv * x[j]; else if ((j & 3) == 2) a2 -= lv * x[j]; else a3 -= lv * x[j]; }
;                 x[i] = (a0 + a1) + (a2 + a3);
; #pragma unroll
;                 for (int q = 0; q < 8; ++q) cur[q] = nxt[q];
;             }
	v_fma_f32 v38, -v102, v0, v24
	v_add_f32_e32 v42, v43, v42
	v_fma_f32 v39, -v103, v1, 0
	v_add_f32_e32 v44, v44, v45
	v_pk_fma_f32 v[40:41], v[104:105], v[2:3], v[46:47] neg_lo:[1,0,0] neg_hi:[1,0,0]
	v_add_f32_e32 v23, v42, v44
	ds_read_b128 v[224:227], v35 offset:56320
	ds_read_b128 v[228:231], v35 offset:56336
	ds_read_b128 v[232:235], v35 offset:56352
	ds_read_b128 v[236:239], v35 offset:56368
	ds_read_b128 v[240:243], v35 offset:56384
	ds_read_b128 v[62:65], v35 offset:56400
	ds_read_b128 v[78:81], v35 offset:56416
	v_pk_fma_f32 v[38:39], v[106:107], v[4:5], v[38:39] neg_lo:[1,0,0] neg_hi:[1,0,0]
	v_pk_fma_f32 v[40:41], v[108:109], v[6:7], v[40:41] neg_lo:[1,0,0] neg_hi:[1,0,0]
	v_pk_fma_f32 v[38:39], v[110:111], v[8:9], v[38:39] neg_lo:[1,0,0] neg_hi:[1,0,0]
	v_pk_fma_f32 v[40:41], v[112:113], v[10:11], v[40:41] neg_lo:[1,0,0] neg_hi:[1,0,0]
	v_pk_fma_f32 v[38:39], v[212:213], v[12:13], v[38:39] neg_lo:[1,0,0] neg_hi:[1,0,0]
	v_pk_fma_f32 v[40:41], v[214:215], v[14:15], v[40:41] neg_lo:[1,0,0] neg_hi:[1,0,0]
	v_pk_fma_f32 v[38:39], v[216:217], v[16:17], v[38:39] neg_lo:[1,0,0] neg_hi:[1,0,0]
	v_pk_fma_f32 v[40:41], v[218:219], v[18:19], v[40:41] neg_lo:[1,0,0] neg_hi:[1,0,0]
	v_pk_fma_f32 v[38:39], v[220:221], v[20:21], v[38:39] neg_lo:[1,0,0] neg_hi:[1,0,0]
	v_pk_fma_f32 v[40:41], v[222:223], v[22:23], v[40:41] neg_lo:[1,0,0] neg_hi:[1,0,0]
	s_waitcnt lgkmcnt(0)
	v_fma_f32 v42, -v224, v0, v25
	v_add_f32_e32 v38, v39, v38
	v_fma_f32 v43, -v225, v1, 0
	v_add_f32_e32 v40, v40, v41
	v_pk_fma_f32 v[44:45], v[226:227], v[2:3], v[46:47] neg_lo:[1,0,0] neg_hi:[1,0,0]
	v_add_f32_e32 v24, v38, v40
	ds_read_b128 v[82:85], v35 offset:56576
	ds_read_b128 v[86:89], v35 offset:56592
	ds_read_b128 v[90:93], v35 offset:56608
	ds_read_b128 v[94:97], v35 offset:56624
	ds_read_b128 v[98:101], v35 offset:56640
	ds_read_b128 v[102:105], v35 offset:56656
	ds_read_b128 v[106:109], v35 offset:56672
	v_pk_fma_f32 v[42:43], v[228:229], v[4:5], v[42:43] neg_lo:[1,0,0] neg_hi:[1,0,0]
	v_pk_fma_f32 v[44:45], v[230:231], v[6:7], v[44:45] neg_lo:[1,0,0] neg_hi:[1,0,0]
	v_pk_fma_f32 v[42:43], v[232:233], v[8:9], v[42:43] neg_lo:[1,0,0] neg_hi:[1,0,0]
	v_pk_fma_f32 v[44:45], v[234:235], v[10:11], v[44:45] neg_lo:[1,0,0] neg_hi:[1,0,0]
	v_pk_fma_f32 v[42:43], v[236:237], v[12:13], v[42:43] neg_lo:[1,0,0] neg_hi:[1,0,0]
	v_pk_fma_f32 v[44:45], v[238:239], v[14:15], v[44:45] neg_lo:[1,0,0] neg_hi:[1,0,0]
	v_pk_fma_f32 v[42:43], v[240:241], v[16:17], v[42:43] neg_lo:[1,0,0] neg_hi:[1,0,0]
	v_pk_fma_f32 v[44:45], v[242:243], v[18:19], v[44:45] neg_lo:[1,0,0] neg_hi:[1,0,0]
	v_pk_fma_f32 v[42:43], v[62:63], v[20:21], v[42:43] neg_lo:[1,0,0] neg_hi:[1,0,0]
	v_pk_fma_f32 v[44:45], v[64:65], v[22:23], v[44:45] neg_lo:[1,0,0] neg_hi:[1,0,0]
	v_pk_fma_f32 v[42:43], v[78:79], v[24:25], v[42:43] neg_lo:[1,0,0] neg_hi:[1,0,0]
	s_waitcnt lgkmcnt(0)
	v_fma_f32 v38, -v82, v0, v26
	v_add_f32_e32 v42, v43, v42
	v_fma_f32 v39, -v83, v1, 0
	v_add_f32_e32 v44, v44, v45
	v_pk_fma_f32 v[40:41], v[84:85], v[2:3], v[46:47] neg_lo:[1,0,0] neg_hi:[1,0,0]
	v_add_f32_e32 v25, v42, v44
	ds_read_b128 v[110:113], v35 offset:56832
	ds_read_b128 v[212:215], v35 offset:56848
	ds_read_b128 v[216:219], v35 offset:56864
	ds_read_b128 v[220:223], v35 offset:56880
	ds_read_b128 v[224:227], v35 offset:56896
	ds_read_b128 v[228:231], v35 offset:56912
	ds_read_b128 v[232:235], v35 offset:56928
	v_pk_fma_f32 v[38:39], v[86:87], v[4:5], v[38:39] neg_lo:[1,0,0] neg_hi:[1,0,0]
	v_pk_fma_f32 v[40:41], v[88:89], v[6:7], v[40:41] neg_lo:[1,0,0] neg_hi:[1,0,0]
	v_pk_fma_f32 v[38:39], v[90:91], v[8:9], v[38:39] neg_lo:[1,0,0] neg_hi:[1,0,0]
	v_pk_fma_f32 v[40:41], v[92:93], v[10:11], v[40:41] neg_lo:[1,0,0] neg_hi:[1,0,0]
	v_pk_fma_f32 v[38:39], v[94:95], v[12:13], v[38:39] neg_lo:[1,0,0] neg_hi:[1,0,0]
	v_pk_fma_f32 v[40:41], v[96:97], v[14:15], v[40:41] neg_lo:[1,0,0] neg_hi:[1,0,0]
	v_pk_fma_f32 v[38:39], v[98:99], v[16:17], v[38:39] neg_lo:[1,0,0] neg_hi:[1,0,0]
	v_pk_fma_f32 v[40:41], v[100:101], v[18:19], v[40:41] neg_lo:[1,0,0] neg_hi:[1,0,0]
	v_pk_fma_f32 v[38:39], v[102:103], v[20:21], v[38:39] neg_lo:[1,0,0] neg_hi:[1,0,0]
	v_pk_fma_f32 v[40:41], v[104:105], v[22:23], v[40:41] neg_lo:[1,0,0] neg_hi:[1,0,0]
	v_pk_fma_f32 v[38:39], v[106:107], v[24:25], v[38:39] neg_lo:[1,0,0] neg_hi:[1,0,0]
	s_waitcnt lgkmcnt(0)
	v_fma_f32 v42, -v110, v0, v27
	v_add_f32_e32 v38, v39, v38
	v_fma_f32 v43, -v111, v1, 0
	v_add_f32_e32 v40, v40, v41
	v_pk_fma_f32 v[44:45], v[112:113], v[2:3], v[46:47] neg_lo:[1,0,0] neg_hi:[1,0,0]
	v_add_f32_e32 v26, v38, v40
	ds_read_b128 v[236:239], v35 offset:57088
	ds_read_b128 v[240:243], v35 offset:57104
	ds_read_b128 v[62:65], v35 offset:57120
	ds_read_b128 v[78:81], v35 offset:57136
	ds_read_b128 v[82:85], v35 offset:57152
	ds_read_b128 v[86:89], v35 offset:57168
	ds_read_b128 v[90:93], v35 offset:57184
	v_pk_fma_f32 v[42:43], v[212:213], v[4:5], v[42:43] neg_lo:[1,0,0] neg_hi:[1,0,0]
	v_pk_fma_f32 v[44:45], v[214:215], v[6:7], v[44:45] neg_lo:[1,0,0] neg_hi:[1,0,0]
	v_pk_fma_f32 v[42:43], v[216:217], v[8:9], v[42:43] neg_lo:[1,0,0] neg_hi:[1,0,0]
	v_pk_fma_f32 v[44:45], v[218:219], v[10:11], v[44:45] neg_lo:[1,0,0] neg_hi:[1,0,0]
	v_pk_fma_f32 v[42:43], v[220:221], v[12:13], v[42:43] neg_lo:[1,0,0] neg_hi:[1,0,0]
	v_pk_fma_f32 v[44:45], v[222:223], v[14:15], v[44:45] neg_lo:[1,0,0] neg_hi:[1,0,0]
	v_pk_fma_f32 v[42:43], v[224:225], v[16:17], v[42:43] neg_lo:[1,0,0] neg_hi:[1,0,0]
	v_pk_fma_f32 v[44:45], v[226:227], v[18:19], v[44:45] neg_lo:[1,0,0] neg_hi:[1,0,0]
	v_pk_fma_f32 v[42:43], v[228:229], v[20:21], v[42:43] neg_lo:[1,0,0] neg_hi:[1,0,0]
	v_pk_fma_f32 v[44:45], v[230:231], v[22:23], v[44:45] neg_lo:[1,0,0] neg_hi:[1,0,0]
	v_pk_fma_f32 v[42:43], v[232:233], v[24:25], v[42:43] neg_lo:[1,0,0] neg_hi:[1,0,0]
	v_pk_fma_f32 v[44:45], v[234:235], v[26:27], v[44:45] neg_lo:[1,0,0] neg_hi:[1,0,0]
	s_waitcnt lgkmcnt(0)
; DI void dn_prep_item(const Params& p, int l, int item, int next_item, u32x4 (&pre)[12], unsigned char* lds, int tid) {
;     ...
;             for (int i = 1; i < 32; ++i) {
;                 if (i < 31) {
; #pragma unroll
;                     for (int q = 0; q < 8; ++q) if (4 * q < i + 1) nxt[q] = *(const f32x4*)(Lb + (i + 1) * 64 + 4 * q);
;                 }
;                 float a0 = x[i], a1 = 0.f, a2 = 0.f, a3 = 0.f;
; #pragma unroll
;                 for (int j = 0; j < i; ++j) { const float lv = cur[j >> 2][j & 3];
;                     if ((j & 3) == 0) a0 -= lv * x[j]; else if ((j & 3) == 1) a1 -= lv * x[j]; else if ((j & 3) == 2) a2 -= lv * x[j]; else a3 -= lv * x[j]; }
;                 x[i] = (a0 + a1) + (a2 + a3);
; #pragma unroll
;                 for (int q = 0; q < 8; ++q) cur[q] = nxt[q];
;             }
;             if (wv < 4) {
; #pragma unroll
;                 for (int i = 0; i < 32; ++i) XS[(r0 + i) * 129 + c] = x[i];
;             } else if (lane < 32) {
	v_fma_f32 v38, -v236, v0, v36
	v_add_f32_e32 v42, v43, v42
	v_fma_f32 v39, -v237, v1, 0
	v_add_f32_e32 v44, v44, v45
	v_pk_fma_f32 v[40:41], v[238:239], v[2:3], v[46:47] neg_lo:[1,0,0] neg_hi:[1,0,0]
	v_add_f32_e32 v27, v42, v44
	ds_read_b128 v[94:97], v35 offset:57344
	ds_read_b128 v[98:101], v35 offset:57360
	ds_read_b128 v[102:105], v35 offset:57376
	ds_read_b128 v[106:109], v35 offset:57392
	ds_read_b128 v[110:113], v35 offset:57408
	ds_read_b128 v[212:215], v35 offset:57424
	ds_read_b128 v[216:219], v35 offset:57440
	ds_read_b128 v[220:223], v35 offset:57456
	v_pk_fma_f32 v[38:39], v[240:241], v[4:5], v[38:39] neg_lo:[1,0,0] neg_hi:[1,0,0]
	v_pk_fma_f32 v[40:41], v[242:243], v[6:7], v[40:41] neg_lo:[1,0,0] neg_hi:[1,0,0]
	v_pk_fma_f32 v[38:39], v[62:63], v[8:9], v[38:39] neg_lo:[1,0,0] neg_hi:[1,0,0]
	v_pk_fma_f32 v[40:41], v[64:65], v[10:11], v[40:41] neg_lo:[1,0,0] neg_hi:[1,0,0]
	v_pk_fma_f32 v[38:39], v[78:79], v[12:13], v[38:39] neg_lo:[1,0,0] neg_hi:[1,0,0]
	v_pk_fma_f32 v[40:41], v[80:81], v[14:15], v[40:41] neg_lo:[1,0,0] neg_hi:[1,0,0]
	v_pk_fma_f32 v[38:39], v[82:83], v[16:17], v[38:39] neg_lo:[1,0,0] neg_hi:[1,0,0]
	v_pk_fma_f32 v[40:41], v[84:85], v[18:19], v[40:41] neg_lo:[1,0,0] neg_hi:[1,0,0]
	v_pk_fma_f32 v[38:39], v[86:87], v[20:21], v[38:39] neg_lo:[1,0,0] neg_hi:[1,0,0]
	v_pk_fma_f32 v[40:41], v[88:89], v[22:23], v[40:41] neg_lo:[1,0,0] neg_hi:[1,0,0]
	v_pk_fma_f32 v[38:39], v[90:91], v[24:25], v[38:39] neg_lo:[1,0,0] neg_hi:[1,0,0]
	v_pk_fma_f32 v[40:41], v[92:93], v[26:27], v[40:41] neg_lo:[1,0,0] neg_hi:[1,0,0]
	s_waitcnt lgkmcnt(0)
	v_fma_f32 v42, -v94, v0, v28
	v_add_f32_e32 v38, v39, v38
	v_fma_f32 v43, -v95, v1, 0
	v_add_f32_e32 v40, v40, v41
	v_pk_fma_f32 v[44:45], v[96:97], v[2:3], v[46:47] neg_lo:[1,0,0] neg_hi:[1,0,0]
	v_add_f32_e32 v36, v38, v40
	ds_read_b128 v[224:227], v35 offset:57600
	ds_read_b128 v[228:231], v35 offset:57616
	ds_read_b128 v[232:235], v35 offset:57632
	ds_read_b128 v[236:239], v35 offset:57648
	ds_read_b128 v[240:243], v35 offset:57664
	ds_read_b128 v[62:65], v35 offset:57680
	ds_read_b128 v[78:81], v35 offset:57696
	ds_read_b128 v[82:85], v35 offset:57712
	v_pk_fma_f32 v[42:43], v[98:99], v[4:5], v[42:43] neg_lo:[1,0,0] neg_hi:[1,0,0]
	v_pk_fma_f32 v[44:45], v[100:101], v[6:7], v[44:45] neg_lo:[1,0,0] neg_hi:[1,0,0]
	v_pk_fma_f32 v[42:43], v[102:103], v[8:9], v[42:43] neg_lo:[1,0,0] neg_hi:[1,0,0]
	v_pk_fma_f32 v[44:45], v[104:105], v[10:11], v[44:45] neg_lo:[1,0,0] neg_hi:[1,0,0]
	v_pk_fma_f32 v[42:43], v[106:107], v[12:13], v[42:43] neg_lo:[1,0,0] neg_hi:[1,0,0]
	v_pk_fma_f32 v[44:45], v[108:109], v[14:15], v[44:45] neg_lo:[1,0,0] neg_hi:[1,0,0]
	v_pk_fma_f32 v[42:43], v[110:111], v[16:17], v[42:43] neg_lo:[1,0,0] neg_hi:[1,0,0]
	v_pk_fma_f32 v[44:45], v[112:113], v[18:19], v[44:45] neg_lo:[1,0,0] neg_hi:[1,0,0]
	v_pk_fma_f32 v[42:43], v[212:213], v[20:21], v[42:43] neg_lo:[1,0,0] neg_hi:[1,0,0]
	v_pk_fma_f32 v[44:45], v[214:215], v[22:23], v[44:45] neg_lo:[1,0,0] neg_hi:[1,0,0]
	v_pk_fma_f32 v[42:43], v[216:217], v[24:25], v[42:43] neg_lo:[1,0,0] neg_hi:[1,0,0]
	v_pk_fma_f32 v[44:45], v[218:219], v[26:27], v[44:45] neg_lo:[1,0,0] neg_hi:[1,0,0]
	v_fma_f32 v42, -v220, v36, v42
	s_waitcnt lgkmcnt(0)
	v_fma_f32 v38, -v224, v0, v29
	v_add_f32_e32 v42, v43, v42
	v_fma_f32 v39, -v225, v1, 0
	v_add_f32_e32 v44, v44, v45
	v_pk_fma_f32 v[40:41], v[226:227], v[2:3], v[46:47] neg_lo:[1,0,0] neg_hi:[1,0,0]
	v_add_f32_e32 v28, v42, v44
	ds_read_b128 v[86:89], v35 offset:57856
	ds_read_b128 v[90:93], v35 offset:57872
	ds_read_b128 v[94:97], v35 offset:57888
	ds_read_b128 v[98:101], v35 offset:57904
	ds_read_b128 v[102:105], v35 offset:57920
	ds_read_b128 v[106:109], v35 offset:57936
	ds_read_b128 v[110:113], v35 offset:57952
	ds_read_b128 v[212:215], v35 offset:57968
	v_pk_fma_f32 v[38:39], v[228:229], v[4:5], v[38:39] neg_lo:[1,0,0] neg_hi:[1,0,0]
	v_pk_fma_f32 v[40:41], v[230:231], v[6:7], v[40:41] neg_lo:[1,0,0] neg_hi:[1,0,0]
	v_pk_fma_f32 v[38:39], v[232:233], v[8:9], v[38:39] neg_lo:[1,0,0] neg_hi:[1,0,0]
	v_pk_fma_f32 v[40:41], v[234:235], v[10:11], v[40:41] neg_lo:[1,0,0] neg_hi:[1,0,0]
	v_pk_fma_f32 v[38:39], v[236:237], v[12:13], v[38:39] neg_lo:[1,0,0] neg_hi:[1,0,0]
	v_pk_fma_f32 v[40:41], v[238:239], v[14:15], v[40:41] neg_lo:[1,0,0] neg_hi:[1,0,0]
	v_pk_fma_f32 v[38:39], v[240:241], v[16:17], v[38:39] neg_lo:[1,0,0] neg_hi:[1,0,0]
	v_pk_fma_f32 v[40:41], v[242:243], v[18:19], v[40:41] neg_lo:[1,0,0] neg_hi:[1,0,0]
	v_pk_fma_f32 v[38:39], v[62:63], v[20:21], v[38:39] neg_lo:[1,0,0] neg_hi:[1,0,0]
	v_pk_fma_f32 v[40:41], v[64:65], v[22:23], v[40:41] neg_lo:[1,0,0] neg_hi:[1,0,0]
	v_pk_fma_f32 v[38:39], v[78:79], v[24:25], v[38:39] neg_lo:[1,0,0] neg_hi:[1,0,0]
	v_pk_fma_f32 v[40:41], v[80:81], v[26:27], v[40:41] neg_lo:[1,0,0] neg_hi:[1,0,0]
	v_fma_f32 v38, -v82, v36, v38
	v_fma_f32 v39, -v83, v28, v39
	s_waitcnt lgkmcnt(0)
	v_fma_f32 v42, -v86, v0, v37
	v_add_f32_e32 v38, v39, v38
	v_fma_f32 v43, -v87, v1, 0
	v_add_f32_e32 v40, v40, v41
	v_pk_fma_f32 v[44:45], v[88:89], v[2:3], v[46:47] neg_lo:[1,0,0] neg_hi:[1,0,0]
	v_add_f32_e32 v29, v38, v40
	v_pk_fma_f32 v[42:43], v[90:91], v[4:5], v[42:43] neg_lo:[1,0,0] neg_hi:[1,0,0]
	v_pk_fma_f32 v[44:45], v[92:93], v[6:7], v[44:45] neg_lo:[1,0,0] neg_hi:[1,0,0]
	v_pk_fma_f32 v[42:43], v[94:95], v[8:9], v[42:43] neg_lo:[1,0,0] neg_hi:[1,0,0]
	v_pk_fma_f32 v[44:45], v[96:97], v[10:11], v[44:45] neg_lo:[1,0,0] neg_hi:[1,0,0]
	v_pk_fma_f32 v[42:43], v[98:99], v[12:13], v[42:43] neg_lo:[1,0,0] neg_hi:[1,0,0]
	v_pk_fma_f32 v[44:45], v[100:101], v[14:15], v[44:45] neg_lo:[1,0,0] neg_hi:[1,0,0]
	v_pk_fma_f32 v[42:43], v[102:103], v[16:17], v[42:43] neg_lo:[1,0,0] neg_hi:[1,0,0]
	v_pk_fma_f32 v[44:45], v[104:105], v[18:19], v[44:45] neg_lo:[1,0,0] neg_hi:[1,0,0]
	v_pk_fma_f32 v[42:43], v[106:107], v[20:21], v[42:43] neg_lo:[1,0,0] neg_hi:[1,0,0]
	v_pk_fma_f32 v[44:45], v[108:109], v[22:23], v[44:45] neg_lo:[1,0,0] neg_hi:[1,0,0]
	v_pk_fma_f32 v[42:43], v[110:111], v[24:25], v[42:43] neg_lo:[1,0,0] neg_hi:[1,0,0]
	v_pk_fma_f32 v[44:45], v[112:113], v[26:27], v[44:45] neg_lo:[1,0,0] neg_hi:[1,0,0]
	v_fma_f32 v42, -v212, v36, v42
	v_fma_f32 v43, -v213, v28, v43
	v_fma_f32 v44, -v214, v29, v44
	v_add_f32_e32 v42, v43, v42
	v_add_f32_e32 v44, v44, v45
	v_add_f32_e32 v35, v42, v44
	s_and_saveexec_b64 s[6:7], vcc
	s_xor_b64 s[6:7], exec, s[6:7]
	s_cbranch_execz .LBB0_498
; DI void dn_prep_item(const Params& p, int l, int item, int next_item, u32x4 (&pre)[12], unsigned char* lds, int tid) {
;     ...
;             if (wv < 4) {
; #pragma unroll
;                 for (int i = 0; i < 32; ++i) XS[(r0 + i) * 129 + c] = x[i];
	v_mul_u32_u24_e32 v30, 0x204, v33
	v_lshlrev_b32_e32 v31, 2, v32
	v_add3_u32 v30, v50, v30, v31
	ds_write2_b32 v30, v0, v1 offset1:129
	v_add_u32_e32 v0, 0x400, v30
	ds_write2_b32 v0, v2, v3 offset0:2 offset1:131
	v_add_u32_e32 v0, 0x800, v30
	ds_write2_b32 v0, v4, v5 offset0:4 offset1:133
	v_add_u32_e32 v0, 0xc00, v30
	ds_write2_b32 v0, v6, v7 offset0:6 offset1:135
	v_add_u32_e32 v0, 0x1000, v30
	ds_write2_b32 v0, v8, v9 offset0:8 offset1:137
	v_add_u32_e32 v0, 0x1400, v30
	ds_write2_b32 v0, v10, v11 offset0:10 offset1:139
	v_add_u32_e32 v0, 0x1800, v30
	ds_write2_b32 v0, v12, v13 offset0:12 offset1:141
	v_add_u32_e32 v0, 0x1c00, v30
	ds_write2_b32 v0, v14, v15 offset0:14 offset1:143
	v_add_u32_e32 v0, 0x2000, v30
	ds_write2_b32 v0, v16, v17 offset0:16 offset1:145
	v_add_u32_e32 v0, 0x2400, v30
	ds_write2_b32 v0, v18, v19 offset0:18 offset1:147
	v_add_u32_e32 v0, 0x2800, v30
	ds_write2_b32 v0, v20, v21 offset0:20 offset1:149
	v_add_u32_e32 v0, 0x2c00, v30
	ds_write2_b32 v0, v22, v23 offset0:22 offset1:151
	v_add_u32_e32 v0, 0x3000, v30
	ds_write2_b32 v0, v24, v25 offset0:24 offset1:153
	v_add_u32_e32 v0, 0x3400, v30
	ds_write2_b32 v0, v26, v27 offset0:26 offset1:155
	v_add_u32_e32 v0, 0x3800, v30
	ds_write2_b32 v0, v36, v28 offset0:28 offset1:157
	v_add_u32_e32 v0, 0x3c00, v30
	ds_write2_b32 v0, v29, v35 offset0:30 offset1:159

; DI void dn_prep_fetch(const Params& p, int item, int tid, u32x4 (&pre)[12]) {
;     const int h = item & 7, n = (item >> 3) & 31, b = item >> 8, i = tid >> 3, d0 = (tid & 7) * 8;
;     const bf16_t* DQKV = (const bf16_t*)(p.ws + OFF_DQKV);
; #pragma unroll
;     for (int mat = 0; mat < 3; ++mat)
; #pragma unroll
;         for (int j = 0; j < 4; ++j) { int t = n * 64 + i - 3 + j; t = t < 0 ? 0 : t; pre[mat * 4 + j] = *(const u32x4*)(DQKV + (size_t)(b * SEQL + t) * 1536 + mat * 512 + h * 64 + d0); }
; }
; DI void dn_prep_item(const Params& p, int l, int item, int next_item, u32x4 (&pre)[12], unsigned char* lds, int tid) {
;     ...
;         {
;             const int c = tid & 127, rg = tid >> 7;
;             float xt[32];
; #pragma unroll
;             for (int k = 0; k < 32; ++k) xt[k] = XS[k * 129 + c];
; #pragma unroll
;             for (int ii = 0; ii < 8; ++ii) { const int i = rg * 8 + ii; float a0 = XS[(32 + i) * 129 + c], a1 = 0.f;
; #pragma unroll
;                 for (int k = 0; k < 32; k += 2) { a0 -= Zs[i * 33 + k] * xt[k]; a1 -= Zs[i * 33 + k + 1] * xt[k + 1]; }
;                 XS[(32 + i) * 129 + c] = a0 + a1; }
;         }
;     }
;     __syncthreads();
;     dn_prep_fetch(p, next_item < 2048 ? next_item : item, tid, pre);
.LBB0_503:
	s_or_b64 exec, exec, s[8:9]
	v_ashrrev_i32_e32 v35, 4, v54
	v_and_b32_e32 v2, 0x7f, v54
	v_and_b32_e32 v38, -8, v35
	s_movk_i32 s12, 0x204
	v_lshl_add_u32 v36, v2, 2, v50
	v_mul_lo_u32 v40, v38, s12
	s_movk_i32 s5, 0x84
	v_add_u32_e32 v41, v36, v40
	v_mad_u64_u32 v[38:39], s[6:7], v38, s5, v[52:53]
	s_waitcnt lgkmcnt(0)
	s_barrier
	v_and_b32_e32 v2, 15, v206
	v_lshrrev_b32_e32 v3, 4, v206
	v_lshrrev_b32_e32 v4, 6, v54
	v_lshl_add_u32 v4, v4, 4, v2
	v_mul_u32_u24_e32 v5, 0x90, v2
	v_lshl_add_u32 v5, v3, 2, v5
	v_add_u32_e32 v5, v5, v52
	v_mul_u32_u24_e32 v6, 0x204, v3
	v_lshl_add_u32 v6, v4, 2, v6
	v_add_u32_e32 v6, v6, v50
	v_mul_u32_u24_e32 v7, 0x810, v3
	v_lshl_add_u32 v7, v4, 2, v7
	v_add_u32_e32 v7, v7, v50
	ds_read_b32 v8, v6
	ds_read_b32 v9, v6 offset:2064
	ds_read_b32 v10, v6 offset:4128
	ds_read_b32 v11, v6 offset:6192
	ds_read_b32 v12, v6 offset:8256
	ds_read_b32 v13, v6 offset:10320
	ds_read_b32 v14, v6 offset:12384
	ds_read_b32 v15, v6 offset:14448
	ds_read_b32 v16, v5
	ds_read_b32 v17, v5 offset:16
	ds_read_b32 v18, v5 offset:32
	ds_read_b32 v19, v5 offset:48
	ds_read_b32 v20, v5 offset:64
	ds_read_b32 v21, v5 offset:80
	ds_read_b32 v22, v5 offset:96
	ds_read_b32 v23, v5 offset:112
	ds_read_b32 v24, v5 offset:2304
	ds_read_b32 v25, v5 offset:2320
	ds_read_b32 v26, v5 offset:2336
	ds_read_b32 v27, v5 offset:2352
	ds_read_b32 v28, v5 offset:2368
	ds_read_b32 v29, v5 offset:2384
	ds_read_b32 v30, v5 offset:2400
	ds_read_b32 v31, v5 offset:2416
	ds_read_b32 v36, v7 offset:16512
	ds_read_b32 v37, v7 offset:17028
	ds_read_b32 v38, v7 offset:17544
	ds_read_b32 v39, v7 offset:18060
	ds_read_b32 v40, v7 offset:24768
	ds_read_b32 v41, v7 offset:25284
	ds_read_b32 v42, v7 offset:25800
	ds_read_b32 v43, v7 offset:26316
	s_waitcnt lgkmcnt(8)
	v_mfma_f32_16x16x4_f32 v[44:47], v16, v8, 0
	v_mfma_f32_16x16x4_f32 v[212:215], v24, v8, 0
	v_mfma_f32_16x16x4_f32 v[44:47], v17, v9, v[44:47]
	v_mfma_f32_16x16x4_f32 v[212:215], v25, v9, v[212:215]
	v_mfma_f32_16x16x4_f32 v[44:47], v18, v10, v[44:47]
	v_mfma_f32_16x16x4_f32 v[212:215], v26, v10, v[212:215]
	v_mfma_f32_16x16x4_f32 v[44:47], v19, v11, v[44:47]
	v_mfma_f32_16x16x4_f32 v[212:215], v27, v11, v[212:215]
	v_mfma_f32_16x16x4_f32 v[44:47], v20, v12, v[44:47]
	v_mfma_f32_16x16x4_f32 v[212:215], v28, v12, v[212:215]
	v_mfma_f32_16x16x4_f32 v[44:47], v21, v13, v[44:47]
	v_mfma_f32_16x16x4_f32 v[212:215], v29, v13, v[212:215]
	v_mfma_f32_16x16x4_f32 v[44:47], v22, v14, v[44:47]
	v_mfma_f32_16x16x4_f32 v[212:215], v30, v14, v[212:215]
	v_mfma_f32_16x16x4_f32 v[44:47], v23, v15, v[44:47]
	v_mfma_f32_16x16x4_f32 v[212:215], v31, v15, v[212:215]
	s_waitcnt lgkmcnt(0)
	s_nop 8
	v_sub_f32_e32 v36, v36, v44
	v_sub_f32_e32 v37, v37, v45
	v_sub_f32_e32 v38, v38, v46
	v_sub_f32_e32 v39, v39, v47
	v_sub_f32_e32 v40, v40, v212
	v_sub_f32_e32 v41, v41, v213
	v_sub_f32_e32 v42, v42, v214
	v_sub_f32_e32 v43, v43, v215
	ds_write_b32 v7, v36 offset:16512
	ds_write_b32 v7, v37 offset:17028
	ds_write_b32 v7, v38 offset:17544
	ds_write_b32 v7, v39 offset:18060
	ds_write_b32 v7, v40 offset:24768
	ds_write_b32 v7, v41 offset:25284
	ds_write_b32 v7, v42 offset:25800
	ds_write_b32 v7, v43 offset:26316
	s_add_i32 s4, s42, s33
	s_cmpk_gt_i32 s4, 0x7ff
	v_and_b32_e32 v66, -16, v77
	v_lshl_add_u64 v[62:63], s[26:27], 0, v[58:59]
	v_or_b32_e32 v58, v66, v61
	v_ashrrev_i32_e32 v57, 31, v56
	s_cselect_b64 s[6:7], -1, 0
	s_cmpk_lt_i32 s4, 0x800
	s_cselect_b32 s5, s4, s42
	s_lshl_b32 s8, s5, 3
	s_lshl_b32 s5, s5, 7
	s_and_b32 s10, s8, 0x7c0
	s_and_b32 s11, s8, 0xfffff800
	s_and_b32 s5, s5, 0x380
	s_add_u32 s8, s29, s5
	s_addc_u32 s9, s40, 0
	v_mov_b32_e32 v35, v165
	s_movk_i32 s5, 0xc00
	v_add_u32_e32 v10, s10, v77
	v_max_i32_e32 v10, 0, v10
	v_add_u32_e32 v10, s11, v10
	v_add3_u32 v8, s10, -3, v77
	v_max_i32_e32 v4, 0, v8
	v_max_i32_e32 v6, -1, v8
	v_max_i32_e32 v8, -2, v8
	v_lshl_add_u64 v[2:3], s[8:9], 0, v[34:35]
	v_add_u32_e32 v4, s11, v4
	v_add3_u32 v6, v6, s11, 1
	v_add3_u32 v8, v8, s11, 2
	v_mad_i64_i32 v[4:5], s[8:9], v4, s5, v[2:3]
	v_mad_i64_i32 v[6:7], s[8:9], v6, s5, v[2:3]
	v_mad_i64_i32 v[8:9], s[8:9], v8, s5, v[2:3]
	v_mad_i64_i32 v[2:3], s[8:9], v10, s5, v[2:3]
	s_waitcnt lgkmcnt(0)
	s_barrier
	s_cmp_lt_u32 s71, 5
	s_cbranch_scc1 .Lpf_w0
	s_waitcnt vmcnt(8)
	s_branch .Lpf_cp

; DI unsigned pk2(float lo, float hi) { f32x2_t v = {lo, hi}; bf16x2_t b = __builtin_convertvector(v, bf16x2_t); return __builtin_bit_cast(unsigned, b); }
; DI void dn_prep_item(const Params& p, int l, int item, int next_item, u32x4 (&pre)[12], unsigned char* lds, int tid) {
;     ...
;     {
;         const int chunk = (b * 8 + h) * 32 + n; unsigned char* base = p.ws + OFF_U + (size_t)chunk * PREP_CHUNK_BYTES;
;         const int f = tid >> 6, m = f >> 1, s = f & 1, r = lane & 15, g = lane >> 4, row = 16 * m + r, c0 = 32 * s + 4 * g, c1 = c0 + 16;
;         u32x4 w;
;         { const float* a = XS + row * 129 + 64; w.x = pk2(a[c0], a[c0 + 1]); w.y = pk2(a[c0 + 2], a[c0 + 3]); w.z = pk2(a[c1], a[c1 + 1]); w.w = pk2(a[c1 + 2], a[c1 + 3]); *(u32x4*)(base + (size_t)tid * 16) = w; }
; #pragma unroll
;         for (int q = 0; q < 2; ++q) { const int idx = tid * 2 + q, wm = idx >> 6, ln = idx & 63, vv = 16 * (wm >> 2) + (ln & 15), r0 = 16 * (wm & 3) + 4 * (ln >> 4);
;             u32x2 o; o.x = pk2(XS[r0 * 129 + vv], XS[(r0 + 1) * 129 + vv]); o.y = pk2(XS[(r0 + 2) * 129 + vv], XS[(r0 + 3) * 129 + vv]); *(u32x2*)(base + 32768 + (size_t)idx * 8) = o; }
;         if (tid == 0) ((float*)(p.ws + OFF_CD))[chunk] = EGs[63];
;     }
.Lpf_cp:
	v_mov_b64_e32 v[2:3], v[116:117]
	v_mov_b64_e32 v[4:5], v[118:119]
	v_mov_b64_e32 v[6:7], v[120:121]
	v_mov_b64_e32 v[8:9], v[122:123]
	v_mov_b64_e32 v[10:11], v[124:125]
	v_mov_b64_e32 v[12:13], v[126:127]
	v_mov_b64_e32 v[14:15], v[128:129]
	v_mov_b64_e32 v[16:17], v[130:131]
	v_mov_b64_e32 v[18:19], v[132:133]
	v_mov_b64_e32 v[20:21], v[134:135]
	v_mov_b64_e32 v[22:23], v[136:137]
	v_mov_b64_e32 v[24:25], v[138:139]
	v_mov_b64_e32 v[26:27], v[140:141]
	v_mov_b64_e32 v[28:29], v[142:143]
	v_mov_b64_e32 v[30:31], v[144:145]
	v_mov_b64_e32 v[32:33], v[146:147]
	v_mov_b64_e32 v[34:35], v[148:149]
	v_mov_b64_e32 v[36:37], v[150:151]
	v_mov_b64_e32 v[38:39], v[152:153]
	v_mov_b64_e32 v[40:41], v[154:155]
	v_mov_b64_e32 v[42:43], v[156:157]
	v_mov_b64_e32 v[44:45], v[158:159]
	v_mov_b64_e32 v[46:47], v[160:161]
	v_mov_b64_e32 v[48:49], v[162:163]
	v_mad_u64_u32 v[58:59], s[8:9], v58, s12, v[50:51]
	v_lshlrev_b32_e32 v59, 7, v60
	v_and_b32_e32 v59, 0x80, v59
	v_and_b32_e32 v60, 48, v54
	v_add3_u32 v64, v58, v59, v60
	ds_read2_b32 v[58:59], v64 offset0:64 offset1:65
	ds_read2_b32 v[60:61], v64 offset0:66 offset1:67
	s_waitcnt lgkmcnt(1)
	v_cvt_pk_bf16_f32 v58, v58, v59
	s_waitcnt lgkmcnt(0)
	v_cvt_pk_bf16_f32 v59, v60, v61
	ds_read2_b32 v[60:61], v64 offset0:80 offset1:81
	ds_read2_b32 v[64:65], v64 offset0:82 offset1:83
	s_waitcnt lgkmcnt(1)
	v_cvt_pk_bf16_f32 v60, v60, v61
	s_waitcnt lgkmcnt(0)
	v_cvt_pk_bf16_f32 v61, v64, v65
	v_lshl_add_u64 v[64:65], v[54:55], 4, v[62:63]
	v_lshrrev_b32_e32 v55, 1, v54
	global_store_dwordx4 v[64:65], v[58:61], off
	v_and_b32_e32 v55, 48, v55
	s_nop 0
	v_lshrrev_b32_e32 v58, 2, v56
	v_and_or_b32 v55, v58, 12, v55
	v_mul_u32_u24_e32 v55, 0x81, v55
	v_and_b32_e32 v58, 14, v56
	v_lshl_add_u32 v58, v58, 2, v50
	v_lshlrev_b32_e32 v59, 2, v66
	v_lshlrev_b32_e32 v55, 2, v55
	v_add3_u32 v55, v58, v59, v55
	ds_read2_b32 v[60:61], v55 offset1:1
	ds_read2_b32 v[64:65], v55 offset0:129 offset1:130
	v_add_u32_e32 v59, 0x408, v55
	v_add_u32_e32 v55, 0x60c, v55
	ds_read2_b32 v[66:67], v59 offset1:1
	ds_read2_b32 v[78:79], v55 offset1:1
	v_lshl_add_u64 v[56:57], v[56:57], 3, v[62:63]
	v_add_co_u32_e32 v56, vcc, 0x8000, v56
	s_waitcnt lgkmcnt(2)
	v_cvt_pk_bf16_f32 v58, v60, v64
	v_addc_co_u32_e32 v57, vcc, 0, v57, vcc
	s_waitcnt lgkmcnt(0)
	v_cvt_pk_bf16_f32 v59, v66, v78
	v_cvt_pk_bf16_f32 v60, v61, v65
	v_cvt_pk_bf16_f32 v61, v67, v79
	v_cmp_eq_u32_e32 vcc, 0, v54
	global_store_dwordx4 v[56:57], v[58:61], off
	s_and_saveexec_b64 s[8:9], vcc
	s_cbranch_execz .LBB0_280
	ds_read_b32 v54, v76
	v_lshl_add_u64 v[0:1], v[0:1], 2, s[38:39]
	s_waitcnt lgkmcnt(0)
	global_store_dword v[0:1], v54, off
	s_branch .LBB0_280
